# strategy: DPP/permlane instead of LDS round trips in GEMM epilogue - v25 + FFN gate/up (SwiGLU) epilogue row-rstd reductions use v_permlane16/32_swap instead of 16 mostly serialized ds_bpermute round
# speedup vs baseline: 1.0053x; 1.0053x over previous
; __device__ __forceinline__ float fsigmoid(float x) { return __builtin_amdgcn_rcpf(1.0f + __builtin_amdgcn_exp2f(-x * LOG2E)); }
; __device__ __forceinline__ void rows_rstd(const float* part, int row0, int fq, float (&rs)[2][4]) {
;     ...
;         for (int m = 0; m < 4; ++m) q[ai][m] = gld((const f32x4*)(part + (size_t)(row0 + ai * HALF + m * 16) * 16 + 4 * fq));
; #pragma unroll
;     for (int ai = 0; ai < 2; ++ai)
; #pragma unroll
;         for (int m = 0; m < 4; ++m) { float t = (q[ai][m].x + q[ai][m].y) + (q[ai][m].z + q[ai][m].w); t += __shfl_xor(t, 16); t += __shfl_xor(t, 32); rs[ai][m] = __builtin_amdgcn_rsqf(t * (1.0f / 1024.0f) + NORM_EPS); }
;     __device__ __forceinline__ void operator()(const f32x4 (&acc)[2][2][4][2], const Unit& u, int wr, int wc, int fr, int fq) const {
;     ...
;             for (int m = 0; m < 4; ++m) { const size_t row = (size_t)(row0 + ai * HALF + m * 16); const float rs = rsv[ai][m]; float r[8];
; #pragma unroll
;                 for (int n = 0; n < 2; ++n) { const f32x4 g = acc[ai][0][m][n] * rs, up = acc[ai][1][m][n] * rs;
; #pragma unroll
;                     for (int e = 0; e < 4; ++e) r[4 * n + e] = g[e] * fsigmoid(g[e]) * up[e]; }
.LBB0_1265:
	v_lshl_add_u32 v176, s7, 8, v165
	v_ashrrev_i32_e32 v177, 31, v176
	v_lshlrev_b64 v[130:131], 6, v[176:177]
	v_lshl_add_u64 v[130:131], v[148:149], 0, v[130:131]
	global_load_dwordx4 v[204:207], v[130:131], off
	v_or_b32_e32 v172, 16, v176
	v_ashrrev_i32_e32 v173, 31, v172
	v_lshlrev_b64 v[130:131], 6, v[172:173]
	v_lshl_add_u64 v[130:131], v[148:149], 0, v[130:131]
	global_load_dwordx4 v[208:211], v[130:131], off
	v_or_b32_e32 v168, 32, v176
	v_ashrrev_i32_e32 v169, 31, v168
	v_lshlrev_b64 v[130:131], 6, v[168:169]
	v_lshl_add_u64 v[130:131], v[148:149], 0, v[130:131]
	global_load_dwordx4 v[212:215], v[130:131], off
	v_or_b32_e32 v162, 48, v176
	v_ashrrev_i32_e32 v163, 31, v162
	v_lshlrev_b64 v[130:131], 6, v[162:163]
	v_lshl_add_u64 v[130:131], v[148:149], 0, v[130:131]
	global_load_dwordx4 v[216:219], v[130:131], off
	v_add_u32_e32 v160, 0x80, v176
	v_ashrrev_i32_e32 v161, 31, v160
	v_lshlrev_b64 v[130:131], 6, v[160:161]
	v_add_u32_e32 v158, 0x90, v176
	v_lshl_add_u64 v[130:131], v[148:149], 0, v[130:131]
	v_ashrrev_i32_e32 v159, 31, v158
	global_load_dwordx4 v[220:223], v[130:131], off
	v_lshlrev_b64 v[130:131], 6, v[158:159]
	v_add_u32_e32 v156, 0xa0, v176
	v_lshl_add_u64 v[130:131], v[148:149], 0, v[130:131]
	v_ashrrev_i32_e32 v157, 31, v156
	global_load_dwordx4 v[138:141], v[130:131], off
	v_lshlrev_b64 v[130:131], 6, v[156:157]
	v_add_u32_e32 v154, 0xb0, v176
	v_lshl_add_u64 v[130:131], v[148:149], 0, v[130:131]
	v_ashrrev_i32_e32 v155, 31, v154
	global_load_dwordx4 v[134:137], v[130:131], off
	v_lshlrev_b64 v[130:131], 6, v[154:155]
	v_lshl_add_u64 v[130:131], v[148:149], 0, v[130:131]
	global_load_dwordx4 v[130:133], v[130:131], off
	v_cmp_lt_i32_e32 vcc, v189, v184
	v_lshl_or_b32 v178, s4, 7, v171
	v_ashrrev_i32_e32 v179, 31, v178
	v_cndmask_b32_e32 v155, v183, v189, vcc
	v_lshlrev_b32_e32 v155, 2, v155
	v_cmp_lt_i32_e32 vcc, v190, v184
	s_movk_i32 s4, 0x1600
	s_waitcnt vmcnt(0)
	v_mov_b32_e32 v180, v205
	v_mov_b32_e32 v181, v206
	v_mov_b32_e32 v205, v207
	v_pk_add_f32 v[180:181], v[180:181], v[204:205]
	v_cndmask_b32_e32 v157, v183, v190, vcc
	v_add_f32_e32 v159, v180, v181
	v_mov_b32_e32 v161, v159
	v_lshlrev_b32_e32 v157, 2, v157
	v_mov_b32_e32 v204, v209
	v_mov_b32_e32 v205, v210
	v_mov_b32_e32 v209, v211
	s_waitcnt lgkmcnt(0)
	s_nop 1
	v_permlane16_swap_b32_e32 v161, v159
	v_add_f32_e32 v159, v159, v161
	v_mov_b32_e32 v161, v159
	v_pk_add_f32 v[204:205], v[204:205], v[208:209]
	s_andn2_b64 vcc, exec, s[40:41]
	s_waitcnt lgkmcnt(0)
	s_nop 1
	v_permlane32_swap_b32_e32 v161, v159
	v_add_f32_e32 v159, v159, v161
	v_fmamk_f32 v159, v159, 0x3a800000, v192
	v_rsq_f32_e32 v180, v159
	v_add_f32_e32 v159, v204, v205
	v_mov_b32_e32 v161, v159
	v_mov_b32_e32 v204, v213
	v_mov_b32_e32 v205, v214
	v_mov_b32_e32 v213, v215
	v_pk_add_f32 v[204:205], v[204:205], v[212:213]
	s_waitcnt lgkmcnt(0)
	s_nop 1
	v_permlane16_swap_b32_e32 v161, v159
	v_add_f32_e32 v159, v159, v161
	v_mov_b32_e32 v161, v159
	s_waitcnt lgkmcnt(0)
	s_nop 1
	v_permlane32_swap_b32_e32 v161, v159
	v_add_f32_e32 v159, v159, v161
	v_fmamk_f32 v159, v159, 0x3a800000, v192
	v_rsq_f32_e32 v174, v159
	v_add_f32_e32 v159, v204, v205
	v_mov_b32_e32 v161, v159
	v_mov_b32_e32 v204, v217
	v_mov_b32_e32 v205, v218
	v_mov_b32_e32 v217, v219
	v_pk_add_f32 v[204:205], v[204:205], v[216:217]
	s_waitcnt lgkmcnt(0)
	s_nop 1
	v_permlane16_swap_b32_e32 v161, v159
	v_add_f32_e32 v159, v159, v161
	v_mov_b32_e32 v161, v159
	s_waitcnt lgkmcnt(0)
	s_nop 1
	v_permlane32_swap_b32_e32 v161, v159
	v_add_f32_e32 v159, v159, v161
	v_fmamk_f32 v159, v159, 0x3a800000, v192
	v_rsq_f32_e32 v170, v159
	v_add_f32_e32 v159, v204, v205
	v_mov_b32_e32 v161, v159
	v_mov_b32_e32 v204, v221
	v_mov_b32_e32 v205, v222
	v_mov_b32_e32 v221, v223
	v_pk_add_f32 v[204:205], v[204:205], v[220:221]
	s_waitcnt lgkmcnt(0)
	s_nop 1
	v_permlane16_swap_b32_e32 v161, v159
	v_add_f32_e32 v159, v159, v161
	v_mov_b32_e32 v161, v159
	s_waitcnt lgkmcnt(0)
	s_nop 1
	v_permlane32_swap_b32_e32 v161, v159
	v_add_f32_e32 v159, v159, v161
	v_fmamk_f32 v159, v159, 0x3a800000, v192
	v_rsq_f32_e32 v166, v159
	v_add_f32_e32 v159, v204, v205
	v_mov_b32_e32 v204, v139
	v_mov_b32_e32 v205, v140
	v_mov_b32_e32 v139, v141
	v_mov_b32_e32 v140, v135
	v_mov_b32_e32 v141, v136
	v_mov_b32_e32 v135, v137
	v_mov_b32_e32 v136, v131
	v_mov_b32_e32 v137, v132
	v_mov_b32_e32 v131, v133
	v_pk_add_f32 v[130:131], v[136:137], v[130:131]
	v_mov_b32_e32 v132, v122
	v_mov_b32_e32 v133, v126
	v_add_f32_e32 v130, v130, v131
	v_pk_mul_f32 v[132:133], v[132:133], v[180:181] op_sel_hi:[1,0]
	v_mov_b32_e32 v131, v130
	v_mul_f32_e32 v122, 0xbfb8aa3b, v133
	v_exp_f32_e32 v122, v122
	v_mov_b32_e32 v126, v123
	v_mov_b32_e32 v161, v159
	s_waitcnt lgkmcnt(1)
	s_nop 1
	v_permlane16_swap_b32_e32 v131, v130
	v_add_f32_e32 v130, v130, v131
	v_add_f32_e32 v122, 1.0, v122
	v_mov_b32_e32 v131, v130
	v_rcp_f32_e32 v122, v122
	s_waitcnt lgkmcnt(1)
	s_nop 1
	v_permlane16_swap_b32_e32 v161, v159
	v_add_f32_e32 v159, v159, v161
	v_mov_b32_e32 v161, v159
	v_pk_add_f32 v[138:139], v[204:205], v[138:139]
	v_mul_f32_e32 v122, v133, v122
	s_waitcnt lgkmcnt(1)
	s_nop 1
	v_permlane32_swap_b32_e32 v131, v130
	v_add_f32_e32 v130, v130, v131
	v_mul_f32_e32 v131, v132, v122
	v_pk_mul_f32 v[122:123], v[126:127], v[180:181] op_sel_hi:[1,0]
	s_waitcnt lgkmcnt(0)
; __device__ __forceinline__ unsigned cvt_pk_bf16(float lo, float hi) { unsigned r; asm volatile("v_cvt_pk_bf16_f32 %0, %1, %2" : "=v"(r) : "v"(lo), "v"(hi)); return r; }
; __device__ __forceinline__ float fsigmoid(float x) { return __builtin_amdgcn_rcpf(1.0f + __builtin_amdgcn_exp2f(-x * LOG2E)); }
; __device__ __forceinline__ void rows_rstd(const float* part, int row0, int fq, float (&rs)[2][4]) {
;     ...
;         for (int m = 0; m < 4; ++m) q[ai][m] = gld((const f32x4*)(part + (size_t)(row0 + ai * HALF + m * 16) * 16 + 4 * fq));
; #pragma unroll
;     for (int ai = 0; ai < 2; ++ai)
; #pragma unroll
;         for (int m = 0; m < 4; ++m) { float t = (q[ai][m].x + q[ai][m].y) + (q[ai][m].z + q[ai][m].w); t += __shfl_xor(t, 16); t += __shfl_xor(t, 32); rs[ai][m] = __builtin_amdgcn_rsqf(t * (1.0f / 1024.0f) + NORM_EPS); }
;     __device__ __forceinline__ void operator()(const f32x4 (&acc)[2][2][4][2], const Unit& u, int wr, int wc, int fr, int fq) const {
;     ...
;             for (int m = 0; m < 4; ++m) { const size_t row = (size_t)(row0 + ai * HALF + m * 16); const float rs = rsv[ai][m]; float r[8];
; #pragma unroll
;                 for (int n = 0; n < 2; ++n) { const f32x4 g = acc[ai][0][m][n] * rs, up = acc[ai][1][m][n] * rs;
; #pragma unroll
;                     for (int e = 0; e < 4; ++e) r[4 * n + e] = g[e] * fsigmoid(g[e]) * up[e]; }
;                 u32x4 w; w.x = cvt_pk_bf16(r[0], r[1]); w.y = cvt_pk_bf16(r[2], r[3]); w.z = cvt_pk_bf16(r[4], r[5]); w.w = cvt_pk_bf16(r[6], r[7]);
;                 gst((u32x4*)(U + row * ldu + f0), w); }
	s_nop 1
	v_permlane32_swap_b32_e32 v161, v159
	v_add_f32_e32 v159, v159, v161
	v_mul_f32_e32 v126, 0xbfb8aa3b, v123
	v_exp_f32_e32 v126, v126
	v_fmamk_f32 v159, v159, 0x3a800000, v192
	v_rsq_f32_e32 v164, v159
	v_add_f32_e32 v138, v138, v139
	v_add_f32_e32 v126, 1.0, v126
	v_rcp_f32_e32 v126, v126
	v_mov_b32_e32 v139, v138
	v_pk_add_f32 v[134:135], v[140:141], v[134:135]
	v_fmamk_f32 v130, v130, 0x3a800000, v192
	v_mul_f32_e32 v123, v123, v126
	v_mul_f32_e32 v126, v122, v123
	v_mov_b32_e32 v122, v124
	v_mov_b32_e32 v123, v128
	v_pk_mul_f32 v[122:123], v[122:123], v[180:181] op_sel_hi:[1,0]
	v_mov_b32_e32 v128, v125
	v_mul_f32_e32 v124, 0xbfb8aa3b, v123
	v_exp_f32_e32 v124, v124
	s_waitcnt lgkmcnt(0)
	s_nop 1
	v_permlane16_swap_b32_e32 v139, v138
	v_add_f32_e32 v138, v138, v139
	v_mov_b32_e32 v139, v138
	v_add_f32_e32 v134, v134, v135
	v_add_f32_e32 v124, 1.0, v124
	v_rcp_f32_e32 v124, v124
	v_mov_b32_e32 v135, v134
	s_waitcnt lgkmcnt(1)
	s_nop 1
	v_permlane32_swap_b32_e32 v139, v138
	v_add_f32_e32 v138, v138, v139
	v_fmamk_f32 v138, v138, 0x3a800000, v192
	v_mul_f32_e32 v123, v123, v124
	v_mul_f32_e32 v124, v122, v123
	v_pk_mul_f32 v[122:123], v[128:129], v[180:181] op_sel_hi:[1,0]
	v_rsq_f32_e32 v138, v138
	v_mul_f32_e32 v125, 0xbfb8aa3b, v123
	v_exp_f32_e32 v125, v125
	s_waitcnt lgkmcnt(0)
	s_nop 1
	v_permlane16_swap_b32_e32 v135, v134
	v_add_f32_e32 v134, v134, v135
	v_mov_b32_e32 v135, v134
	v_rsq_f32_e32 v130, v130
	v_add_f32_e32 v125, 1.0, v125
	v_rcp_f32_e32 v125, v125
	s_waitcnt lgkmcnt(0)
	s_nop 1
	v_permlane32_swap_b32_e32 v135, v134
	v_add_f32_e32 v134, v134, v135
	v_fmamk_f32 v134, v134, 0x3a800000, v192
	v_mul_f32_e32 v123, v123, v125
	v_mul_f32_e32 v125, v122, v123
	v_mov_b32_e32 v122, v114
	v_mov_b32_e32 v123, v118
	v_pk_mul_f32 v[122:123], v[122:123], v[180:181] op_sel_hi:[1,0]
	v_mov_b32_e32 v118, v115
	v_mul_f32_e32 v114, 0xbfb8aa3b, v123
	v_exp_f32_e32 v114, v114
	v_rsq_f32_e32 v134, v134
	v_add_f32_e32 v114, 1.0, v114
	v_rcp_f32_e32 v114, v114
	s_nop 0
	v_mul_f32_e32 v114, v123, v114
	v_mul_f32_e32 v122, v122, v114
	v_pk_mul_f32 v[114:115], v[118:119], v[180:181] op_sel_hi:[1,0]
	s_nop 0
	v_mul_f32_e32 v118, 0xbfb8aa3b, v115
	v_exp_f32_e32 v118, v118
	s_nop 0
	v_add_f32_e32 v118, 1.0, v118
	v_rcp_f32_e32 v118, v118
	s_nop 0
	v_mul_f32_e32 v115, v115, v118
	v_mul_f32_e32 v123, v114, v115
	v_mov_b32_e32 v114, v116
	v_mov_b32_e32 v115, v120
	v_pk_mul_f32 v[114:115], v[114:115], v[180:181] op_sel_hi:[1,0]
	v_mov_b32_e32 v120, v117
	v_mul_f32_e32 v116, 0xbfb8aa3b, v115
	v_exp_f32_e32 v116, v116
	v_cvt_pk_bf16_f32 v118, v131, v126
	v_cvt_pk_bf16_f32 v119, v124, v125
	s_nop 0
	v_add_f32_e32 v116, 1.0, v116
	v_rcp_f32_e32 v116, v116
	s_nop 0
	v_mul_f32_e32 v115, v115, v116
	v_mul_f32_e32 v116, v114, v115
	v_pk_mul_f32 v[114:115], v[120:121], v[180:181] op_sel_hi:[1,0]
	v_cvt_pk_bf16_f32 v120, v122, v123
	s_nop 0
	v_mul_f32_e32 v117, 0xbfb8aa3b, v115
	v_exp_f32_e32 v117, v117
	s_nop 0
	v_add_f32_e32 v117, 1.0, v117
	v_rcp_f32_e32 v117, v117
	s_nop 0
	v_mul_f32_e32 v115, v115, v117
	v_mul_f32_e32 v114, v114, v115
	v_cvt_pk_bf16_f32 v121, v116, v114
	v_mov_b64_e32 v[114:115], s[10:11]
	v_mad_i64_i32 v[122:123], s[20:21], v176, s4, v[114:115]
	v_lshlrev_b64 v[116:117], 1, v[178:179]
	v_lshl_add_u64 v[122:123], v[122:123], 0, v[116:117]
	global_store_dwordx4 v[122:123], v[118:121], off
	s_nop 1
	v_mov_b32_e32 v118, v106
	v_mov_b32_e32 v119, v110
	v_pk_mul_f32 v[118:119], v[118:119], v[174:175] op_sel_hi:[1,0]
	v_mov_b32_e32 v110, v107
	v_mul_f32_e32 v106, 0xbfb8aa3b, v119
	v_exp_f32_e32 v106, v106
	s_nop 0
	v_add_f32_e32 v106, 1.0, v106
	v_rcp_f32_e32 v106, v106
	s_nop 0
	v_mul_f32_e32 v106, v119, v106
	v_mul_f32_e32 v118, v118, v106
	v_pk_mul_f32 v[106:107], v[110:111], v[174:175] op_sel_hi:[1,0]
	s_nop 0
	v_mul_f32_e32 v110, 0xbfb8aa3b, v107
	v_exp_f32_e32 v110, v110
	s_nop 0
	v_add_f32_e32 v110, 1.0, v110
	v_rcp_f32_e32 v110, v110
	s_nop 0
	v_mul_f32_e32 v107, v107, v110
	v_mul_f32_e32 v110, v106, v107
	v_mov_b32_e32 v106, v108
	v_mov_b32_e32 v107, v112
	v_pk_mul_f32 v[106:107], v[106:107], v[174:175] op_sel_hi:[1,0]
	v_mov_b32_e32 v112, v109
	v_mul_f32_e32 v108, 0xbfb8aa3b, v107
	v_exp_f32_e32 v108, v108
	s_nop 0
	v_add_f32_e32 v108, 1.0, v108
	v_rcp_f32_e32 v108, v108
	s_nop 0
	v_mul_f32_e32 v107, v107, v108
	v_mul_f32_e32 v108, v106, v107
	v_pk_mul_f32 v[106:107], v[112:113], v[174:175] op_sel_hi:[1,0]
	s_nop 0
	v_mul_f32_e32 v109, 0xbfb8aa3b, v107
	v_exp_f32_e32 v109, v109
	s_nop 0
	v_add_f32_e32 v109, 1.0, v109
	v_rcp_f32_e32 v109, v109
	s_nop 0
	v_mul_f32_e32 v107, v107, v109
	v_mul_f32_e32 v109, v106, v107
	v_mov_b32_e32 v106, v98
	v_mov_b32_e32 v107, v102
	v_pk_mul_f32 v[106:107], v[106:107], v[174:175] op_sel_hi:[1,0]
	v_mov_b32_e32 v102, v99
	v_mul_f32_e32 v98, 0xbfb8aa3b, v107
	v_exp_f32_e32 v98, v98
	s_nop 0
	v_add_f32_e32 v98, 1.0, v98
	v_rcp_f32_e32 v98, v98
	s_nop 0
	v_mul_f32_e32 v98, v107, v98
	v_mul_f32_e32 v106, v106, v98
	v_pk_mul_f32 v[98:99], v[102:103], v[174:175] op_sel_hi:[1,0]
	s_nop 0
	v_mul_f32_e32 v102, 0xbfb8aa3b, v99
	v_exp_f32_e32 v102, v102
	s_nop 0
	v_add_f32_e32 v102, 1.0, v102
	v_rcp_f32_e32 v102, v102
	s_nop 0
	v_mul_f32_e32 v99, v99, v102
	v_mul_f32_e32 v102, v98, v99
	v_mov_b32_e32 v98, v100
	v_mov_b32_e32 v99, v104
	v_pk_mul_f32 v[98:99], v[98:99], v[174:175] op_sel_hi:[1,0]
	v_mov_b32_e32 v104, v101
	v_mul_f32_e32 v100, 0xbfb8aa3b, v99
	v_exp_f32_e32 v100, v100
	s_nop 0
	v_add_f32_e32 v100, 1.0, v100
	v_rcp_f32_e32 v100, v100
	s_nop 0
	v_mul_f32_e32 v99, v99, v100
	v_mul_f32_e32 v103, v98, v99
	v_pk_mul_f32 v[98:99], v[104:105], v[174:175] op_sel_hi:[1,0]
	s_nop 0
	v_mul_f32_e32 v100, 0xbfb8aa3b, v99
; __device__ __forceinline__ unsigned cvt_pk_bf16(float lo, float hi) { unsigned r; asm volatile("v_cvt_pk_bf16_f32 %0, %1, %2" : "=v"(r) : "v"(lo), "v"(hi)); return r; }
; __device__ __forceinline__ float fsigmoid(float x) { return __builtin_amdgcn_rcpf(1.0f + __builtin_amdgcn_exp2f(-x * LOG2E)); }
;     __device__ __forceinline__ void operator()(const f32x4 (&acc)[2][2][4][2], const Unit& u, int wr, int wc, int fr, int fq) const {
;     ...
; #pragma unroll
;         for (int ai = 0; ai < 2; ++ai)
; #pragma unroll
;             for (int m = 0; m < 4; ++m) { const size_t row = (size_t)(row0 + ai * HALF + m * 16); const float rs = rsv[ai][m]; float r[8];
; #pragma unroll
;                 for (int n = 0; n < 2; ++n) { const f32x4 g = acc[ai][0][m][n] * rs, up = acc[ai][1][m][n] * rs;
; #pragma unroll
;                     for (int e = 0; e < 4; ++e) r[4 * n + e] = g[e] * fsigmoid(g[e]) * up[e]; }
;                 u32x4 w; w.x = cvt_pk_bf16(r[0], r[1]); w.y = cvt_pk_bf16(r[2], r[3]); w.z = cvt_pk_bf16(r[4], r[5]); w.w = cvt_pk_bf16(r[6], r[7]);
;                 gst((u32x4*)(U + row * ldu + f0), w); }
	v_exp_f32_e32 v100, v100
	s_nop 0
	v_add_f32_e32 v100, 1.0, v100
	v_rcp_f32_e32 v100, v100
	s_nop 0
	v_mul_f32_e32 v99, v99, v100
	v_mul_f32_e32 v101, v98, v99
	v_cvt_pk_bf16_f32 v98, v118, v110
	v_cvt_pk_bf16_f32 v99, v108, v109
	v_cvt_pk_bf16_f32 v100, v106, v102
	v_cvt_pk_bf16_f32 v101, v103, v101
	v_mad_i64_i32 v[102:103], s[20:21], v172, s4, v[114:115]
	v_lshl_add_u64 v[102:103], v[102:103], 0, v[116:117]
	global_store_dwordx4 v[102:103], v[98:101], off
	s_nop 1
	v_mov_b32_e32 v98, v90
	v_mov_b32_e32 v99, v94
	v_pk_mul_f32 v[98:99], v[98:99], v[170:171] op_sel_hi:[1,0]
	v_mov_b32_e32 v94, v91
	v_mul_f32_e32 v90, 0xbfb8aa3b, v99
	v_exp_f32_e32 v90, v90
	s_nop 0
	v_add_f32_e32 v90, 1.0, v90
	v_rcp_f32_e32 v90, v90
	s_nop 0
	v_mul_f32_e32 v90, v99, v90
	v_mul_f32_e32 v98, v98, v90
	v_pk_mul_f32 v[90:91], v[94:95], v[170:171] op_sel_hi:[1,0]
	s_nop 0
	v_mul_f32_e32 v94, 0xbfb8aa3b, v91
	v_exp_f32_e32 v94, v94
	s_nop 0
	v_add_f32_e32 v94, 1.0, v94
	v_rcp_f32_e32 v94, v94
	s_nop 0
	v_mul_f32_e32 v91, v91, v94
	v_mul_f32_e32 v94, v90, v91
	v_mov_b32_e32 v90, v92
	v_mov_b32_e32 v91, v96
	v_pk_mul_f32 v[90:91], v[90:91], v[170:171] op_sel_hi:[1,0]
	v_mov_b32_e32 v96, v93
	v_mul_f32_e32 v92, 0xbfb8aa3b, v91
	v_exp_f32_e32 v92, v92
	s_nop 0
	v_add_f32_e32 v92, 1.0, v92
	v_rcp_f32_e32 v92, v92
	s_nop 0
	v_mul_f32_e32 v91, v91, v92
	v_mul_f32_e32 v92, v90, v91
	v_pk_mul_f32 v[90:91], v[96:97], v[170:171] op_sel_hi:[1,0]
	s_nop 0
	v_mul_f32_e32 v93, 0xbfb8aa3b, v91
	v_exp_f32_e32 v93, v93
	s_nop 0
	v_add_f32_e32 v93, 1.0, v93
	v_rcp_f32_e32 v93, v93
	s_nop 0
	v_mul_f32_e32 v91, v91, v93
	v_mul_f32_e32 v93, v90, v91
	v_mov_b32_e32 v90, v82
	v_mov_b32_e32 v91, v86
	v_pk_mul_f32 v[90:91], v[90:91], v[170:171] op_sel_hi:[1,0]
	v_mov_b32_e32 v86, v83
	v_mul_f32_e32 v82, 0xbfb8aa3b, v91
	v_exp_f32_e32 v82, v82
	s_nop 0
	v_add_f32_e32 v82, 1.0, v82
	v_rcp_f32_e32 v82, v82
	s_nop 0
	v_mul_f32_e32 v82, v91, v82
	v_mul_f32_e32 v90, v90, v82
	v_pk_mul_f32 v[82:83], v[86:87], v[170:171] op_sel_hi:[1,0]
	s_nop 0
	v_mul_f32_e32 v86, 0xbfb8aa3b, v83
	v_exp_f32_e32 v86, v86
	s_nop 0
	v_add_f32_e32 v86, 1.0, v86
	v_rcp_f32_e32 v86, v86
	s_nop 0
	v_mul_f32_e32 v83, v83, v86
	v_mul_f32_e32 v86, v82, v83
	v_mov_b32_e32 v82, v84
	v_mov_b32_e32 v83, v88
	v_pk_mul_f32 v[82:83], v[82:83], v[170:171] op_sel_hi:[1,0]
	v_mov_b32_e32 v88, v85
	v_mul_f32_e32 v84, 0xbfb8aa3b, v83
	v_exp_f32_e32 v84, v84
	s_nop 0
	v_add_f32_e32 v84, 1.0, v84
	v_rcp_f32_e32 v84, v84
	s_nop 0
	v_mul_f32_e32 v83, v83, v84
	v_mul_f32_e32 v87, v82, v83
	v_pk_mul_f32 v[82:83], v[88:89], v[170:171] op_sel_hi:[1,0]
	s_nop 0
	v_mul_f32_e32 v84, 0xbfb8aa3b, v83
	v_exp_f32_e32 v84, v84
	s_nop 0
	v_add_f32_e32 v84, 1.0, v84
	v_rcp_f32_e32 v84, v84
	s_nop 0
	v_mul_f32_e32 v83, v83, v84
	v_mul_f32_e32 v85, v82, v83
	v_cvt_pk_bf16_f32 v82, v98, v94
	v_cvt_pk_bf16_f32 v83, v92, v93
	v_cvt_pk_bf16_f32 v84, v90, v86
	v_cvt_pk_bf16_f32 v85, v87, v85
	v_mad_i64_i32 v[86:87], s[20:21], v168, s4, v[114:115]
	v_lshl_add_u64 v[86:87], v[86:87], 0, v[116:117]
	global_store_dwordx4 v[86:87], v[82:85], off
	s_nop 1
	v_mov_b32_e32 v82, v74
	v_mov_b32_e32 v83, v78
	v_pk_mul_f32 v[82:83], v[82:83], v[166:167] op_sel_hi:[1,0]
	v_mov_b32_e32 v78, v75
	v_mul_f32_e32 v74, 0xbfb8aa3b, v83
	v_exp_f32_e32 v74, v74
	s_nop 0
	v_add_f32_e32 v74, 1.0, v74
	v_rcp_f32_e32 v74, v74
	s_nop 0
	v_mul_f32_e32 v74, v83, v74
	v_mul_f32_e32 v82, v82, v74
	v_pk_mul_f32 v[74:75], v[78:79], v[166:167] op_sel_hi:[1,0]
	s_nop 0
	v_mul_f32_e32 v78, 0xbfb8aa3b, v75
	v_exp_f32_e32 v78, v78
	s_nop 0
	v_add_f32_e32 v78, 1.0, v78
	v_rcp_f32_e32 v78, v78
	s_nop 0
	v_mul_f32_e32 v75, v75, v78
	v_mul_f32_e32 v78, v74, v75
	v_mov_b32_e32 v74, v76
	v_mov_b32_e32 v75, v80
	v_pk_mul_f32 v[74:75], v[74:75], v[166:167] op_sel_hi:[1,0]
	v_mov_b32_e32 v80, v77
	v_mul_f32_e32 v76, 0xbfb8aa3b, v75
	v_exp_f32_e32 v76, v76
	s_nop 0
	v_add_f32_e32 v76, 1.0, v76
	v_rcp_f32_e32 v76, v76
	s_nop 0
	v_mul_f32_e32 v75, v75, v76
	v_mul_f32_e32 v76, v74, v75
	v_pk_mul_f32 v[74:75], v[80:81], v[166:167] op_sel_hi:[1,0]
	s_nop 0
	v_mul_f32_e32 v77, 0xbfb8aa3b, v75
	v_exp_f32_e32 v77, v77
	s_nop 0
	v_add_f32_e32 v77, 1.0, v77
	v_rcp_f32_e32 v77, v77
	s_nop 0
	v_mul_f32_e32 v75, v75, v77
	v_mul_f32_e32 v77, v74, v75
	v_mov_b32_e32 v74, v66
	v_mov_b32_e32 v75, v70
	v_pk_mul_f32 v[74:75], v[74:75], v[166:167] op_sel_hi:[1,0]
	v_mov_b32_e32 v70, v67
	v_mul_f32_e32 v66, 0xbfb8aa3b, v75
	v_exp_f32_e32 v66, v66
	s_nop 0
	v_add_f32_e32 v66, 1.0, v66
	v_rcp_f32_e32 v66, v66
	s_nop 0
	v_mul_f32_e32 v66, v75, v66
	v_mul_f32_e32 v74, v74, v66
	v_pk_mul_f32 v[66:67], v[70:71], v[166:167] op_sel_hi:[1,0]
	s_nop 0
	v_mul_f32_e32 v70, 0xbfb8aa3b, v67
	v_exp_f32_e32 v70, v70
	s_nop 0
	v_add_f32_e32 v70, 1.0, v70
	v_rcp_f32_e32 v70, v70
	s_nop 0
	v_mul_f32_e32 v67, v67, v70
	v_mul_f32_e32 v70, v66, v67
	v_mov_b32_e32 v66, v68
	v_mov_b32_e32 v67, v72
	v_pk_mul_f32 v[66:67], v[66:67], v[166:167] op_sel_hi:[1,0]
	v_mov_b32_e32 v72, v69
	v_mul_f32_e32 v68, 0xbfb8aa3b, v67
	v_exp_f32_e32 v68, v68
	s_nop 0
	v_add_f32_e32 v68, 1.0, v68
	v_rcp_f32_e32 v68, v68
	s_nop 0
	v_mul_f32_e32 v67, v67, v68
	v_mul_f32_e32 v71, v66, v67
	v_pk_mul_f32 v[66:67], v[72:73], v[166:167] op_sel_hi:[1,0]
	s_nop 0
	v_mul_f32_e32 v68, 0xbfb8aa3b, v67
	v_exp_f32_e32 v68, v68
	s_nop 0
	v_add_f32_e32 v68, 1.0, v68
	v_rcp_f32_e32 v68, v68
	s_nop 0
	v_mul_f32_e32 v67, v67, v68
	v_mul_f32_e32 v69, v66, v67
	v_cvt_pk_bf16_f32 v66, v82, v78
	v_cvt_pk_bf16_f32 v67, v76, v77
	v_cvt_pk_bf16_f32 v68, v74, v70
	v_cvt_pk_bf16_f32 v69, v71, v69
	v_mad_i64_i32 v[70:71], s[20:21], v162, s4, v[114:115]
	v_lshl_add_u64 v[70:71], v[70:71], 0, v[116:117]
; __device__ __forceinline__ unsigned cvt_pk_bf16(float lo, float hi) { unsigned r; asm volatile("v_cvt_pk_bf16_f32 %0, %1, %2" : "=v"(r) : "v"(lo), "v"(hi)); return r; }
; __device__ __forceinline__ float fsigmoid(float x) { return __builtin_amdgcn_rcpf(1.0f + __builtin_amdgcn_exp2f(-x * LOG2E)); }
;     __device__ __forceinline__ void operator()(const f32x4 (&acc)[2][2][4][2], const Unit& u, int wr, int wc, int fr, int fq) const {
;     ...
; #pragma unroll
;         for (int ai = 0; ai < 2; ++ai)
; #pragma unroll
;             for (int m = 0; m < 4; ++m) { const size_t row = (size_t)(row0 + ai * HALF + m * 16); const float rs = rsv[ai][m]; float r[8];
; #pragma unroll
;                 for (int n = 0; n < 2; ++n) { const f32x4 g = acc[ai][0][m][n] * rs, up = acc[ai][1][m][n] * rs;
; #pragma unroll
;                     for (int e = 0; e < 4; ++e) r[4 * n + e] = g[e] * fsigmoid(g[e]) * up[e]; }
;                 u32x4 w; w.x = cvt_pk_bf16(r[0], r[1]); w.y = cvt_pk_bf16(r[2], r[3]); w.z = cvt_pk_bf16(r[4], r[5]); w.w = cvt_pk_bf16(r[6], r[7]);
;                 gst((u32x4*)(U + row * ldu + f0), w); }
	global_store_dwordx4 v[70:71], v[66:69], off
	s_nop 1
	v_mov_b32_e32 v66, v58
	v_mov_b32_e32 v67, v62
	v_pk_mul_f32 v[66:67], v[66:67], v[164:165] op_sel_hi:[1,0]
	v_mov_b32_e32 v62, v59
	v_mul_f32_e32 v58, 0xbfb8aa3b, v67
	v_exp_f32_e32 v58, v58
	s_nop 0
	v_add_f32_e32 v58, 1.0, v58
	v_rcp_f32_e32 v58, v58
	s_nop 0
	v_mul_f32_e32 v58, v67, v58
	v_mul_f32_e32 v66, v66, v58
	v_pk_mul_f32 v[58:59], v[62:63], v[164:165] op_sel_hi:[1,0]
	s_nop 0
	v_mul_f32_e32 v62, 0xbfb8aa3b, v59
	v_exp_f32_e32 v62, v62
	s_nop 0
	v_add_f32_e32 v62, 1.0, v62
	v_rcp_f32_e32 v62, v62
	s_nop 0
	v_mul_f32_e32 v59, v59, v62
	v_mul_f32_e32 v62, v58, v59
	v_mov_b32_e32 v58, v60
	v_mov_b32_e32 v59, v64
	v_pk_mul_f32 v[58:59], v[58:59], v[164:165] op_sel_hi:[1,0]
	v_mov_b32_e32 v64, v61
	v_mul_f32_e32 v60, 0xbfb8aa3b, v59
	v_exp_f32_e32 v60, v60
	s_nop 0
	v_add_f32_e32 v60, 1.0, v60
	v_rcp_f32_e32 v60, v60
	s_nop 0
	v_mul_f32_e32 v59, v59, v60
	v_mul_f32_e32 v60, v58, v59
	v_pk_mul_f32 v[58:59], v[64:65], v[164:165] op_sel_hi:[1,0]
	s_nop 0
	v_mul_f32_e32 v61, 0xbfb8aa3b, v59
	v_exp_f32_e32 v61, v61
	s_nop 0
	v_add_f32_e32 v61, 1.0, v61
	v_rcp_f32_e32 v61, v61
	s_nop 0
	v_mul_f32_e32 v59, v59, v61
	v_mul_f32_e32 v61, v58, v59
	v_mov_b32_e32 v58, v50
	v_mov_b32_e32 v59, v54
	v_pk_mul_f32 v[58:59], v[58:59], v[164:165] op_sel_hi:[1,0]
	v_mov_b32_e32 v54, v51
	v_mul_f32_e32 v50, 0xbfb8aa3b, v59
	v_exp_f32_e32 v50, v50
	s_nop 0
	v_add_f32_e32 v50, 1.0, v50
	v_rcp_f32_e32 v50, v50
	s_nop 0
	v_mul_f32_e32 v50, v59, v50
	v_mul_f32_e32 v58, v58, v50
	v_pk_mul_f32 v[50:51], v[54:55], v[164:165] op_sel_hi:[1,0]
	s_nop 0
	v_mul_f32_e32 v54, 0xbfb8aa3b, v51
	v_exp_f32_e32 v54, v54
	s_nop 0
	v_add_f32_e32 v54, 1.0, v54
	v_rcp_f32_e32 v54, v54
	s_nop 0
	v_mul_f32_e32 v51, v51, v54
	v_mul_f32_e32 v54, v50, v51
	v_mov_b32_e32 v50, v52
	v_mov_b32_e32 v51, v56
	v_pk_mul_f32 v[50:51], v[50:51], v[164:165] op_sel_hi:[1,0]
	v_mov_b32_e32 v56, v53
	v_mul_f32_e32 v52, 0xbfb8aa3b, v51
	v_exp_f32_e32 v52, v52
	s_nop 0
	v_add_f32_e32 v52, 1.0, v52
	v_rcp_f32_e32 v52, v52
	s_nop 0
	v_mul_f32_e32 v51, v51, v52
	v_mul_f32_e32 v55, v50, v51
	v_pk_mul_f32 v[50:51], v[56:57], v[164:165] op_sel_hi:[1,0]
	s_nop 0
	v_mul_f32_e32 v52, 0xbfb8aa3b, v51
	v_exp_f32_e32 v52, v52
	s_nop 0
	v_add_f32_e32 v52, 1.0, v52
	v_rcp_f32_e32 v52, v52
	s_nop 0
	v_mul_f32_e32 v51, v51, v52
	v_mul_f32_e32 v53, v50, v51
	v_cvt_pk_bf16_f32 v50, v66, v62
	v_cvt_pk_bf16_f32 v51, v60, v61
	v_cvt_pk_bf16_f32 v52, v58, v54
	v_cvt_pk_bf16_f32 v53, v55, v53
	v_mad_i64_i32 v[54:55], s[20:21], v160, s4, v[114:115]
	v_lshl_add_u64 v[54:55], v[54:55], 0, v[116:117]
	global_store_dwordx4 v[54:55], v[50:53], off
	s_nop 1
	v_mov_b32_e32 v50, v42
	v_mov_b32_e32 v51, v46
	v_pk_mul_f32 v[50:51], v[50:51], v[138:139] op_sel_hi:[1,0]
	v_mov_b32_e32 v46, v43
	v_mul_f32_e32 v42, 0xbfb8aa3b, v51
	v_exp_f32_e32 v42, v42
	s_nop 0
	v_add_f32_e32 v42, 1.0, v42
	v_rcp_f32_e32 v42, v42
	s_nop 0
	v_mul_f32_e32 v42, v51, v42
	v_mul_f32_e32 v50, v50, v42
	v_pk_mul_f32 v[42:43], v[46:47], v[138:139] op_sel_hi:[1,0]
	s_nop 0
	v_mul_f32_e32 v46, 0xbfb8aa3b, v43
	v_exp_f32_e32 v46, v46
	s_nop 0
	v_add_f32_e32 v46, 1.0, v46
	v_rcp_f32_e32 v46, v46
	s_nop 0
	v_mul_f32_e32 v43, v43, v46
	v_mul_f32_e32 v46, v42, v43
	v_mov_b32_e32 v42, v44
	v_mov_b32_e32 v43, v48
	v_pk_mul_f32 v[42:43], v[42:43], v[138:139] op_sel_hi:[1,0]
	v_mov_b32_e32 v48, v45
	v_mul_f32_e32 v44, 0xbfb8aa3b, v43
	v_exp_f32_e32 v44, v44
	s_nop 0
	v_add_f32_e32 v44, 1.0, v44
	v_rcp_f32_e32 v44, v44
	s_nop 0
	v_mul_f32_e32 v43, v43, v44
	v_mul_f32_e32 v44, v42, v43
	v_pk_mul_f32 v[42:43], v[48:49], v[138:139] op_sel_hi:[1,0]
	s_nop 0
	v_mul_f32_e32 v45, 0xbfb8aa3b, v43
	v_exp_f32_e32 v45, v45
	s_nop 0
	v_add_f32_e32 v45, 1.0, v45
	v_rcp_f32_e32 v45, v45
	s_nop 0
	v_mul_f32_e32 v43, v43, v45
	v_mul_f32_e32 v45, v42, v43
	v_mov_b32_e32 v42, v34
	v_mov_b32_e32 v43, v38
	v_pk_mul_f32 v[42:43], v[42:43], v[138:139] op_sel_hi:[1,0]
	v_mov_b32_e32 v38, v35
	v_mul_f32_e32 v34, 0xbfb8aa3b, v43
	v_exp_f32_e32 v34, v34
	s_nop 0
	v_add_f32_e32 v34, 1.0, v34
	v_rcp_f32_e32 v34, v34
	s_nop 0
	v_mul_f32_e32 v34, v43, v34
	v_mul_f32_e32 v42, v42, v34
	v_pk_mul_f32 v[34:35], v[38:39], v[138:139] op_sel_hi:[1,0]
	s_nop 0
	v_mul_f32_e32 v38, 0xbfb8aa3b, v35
	v_exp_f32_e32 v38, v38
	s_nop 0
	v_add_f32_e32 v38, 1.0, v38
	v_rcp_f32_e32 v38, v38
	s_nop 0
	v_mul_f32_e32 v35, v35, v38
	v_mul_f32_e32 v38, v34, v35
	v_mov_b32_e32 v34, v36
	v_mov_b32_e32 v35, v40
	v_pk_mul_f32 v[34:35], v[34:35], v[138:139] op_sel_hi:[1,0]
	v_mov_b32_e32 v40, v37
	v_mul_f32_e32 v36, 0xbfb8aa3b, v35
	v_exp_f32_e32 v36, v36
	s_nop 0
	v_add_f32_e32 v36, 1.0, v36
	v_rcp_f32_e32 v36, v36
	s_nop 0
	v_mul_f32_e32 v35, v35, v36
	v_mul_f32_e32 v39, v34, v35
	v_pk_mul_f32 v[34:35], v[40:41], v[138:139] op_sel_hi:[1,0]
	s_nop 0
	v_mul_f32_e32 v36, 0xbfb8aa3b, v35
	v_exp_f32_e32 v36, v36
	s_nop 0
	v_add_f32_e32 v36, 1.0, v36
	v_rcp_f32_e32 v36, v36
	s_nop 0
	v_mul_f32_e32 v35, v35, v36
	v_mul_f32_e32 v37, v34, v35
	v_cvt_pk_bf16_f32 v34, v50, v46
	v_cvt_pk_bf16_f32 v35, v44, v45
	v_cvt_pk_bf16_f32 v36, v42, v38
	v_cvt_pk_bf16_f32 v37, v39, v37
	v_mad_i64_i32 v[38:39], s[20:21], v158, s4, v[114:115]
	v_lshl_add_u64 v[38:39], v[38:39], 0, v[116:117]
	global_store_dwordx4 v[38:39], v[34:37], off
; __device__ __forceinline__ unsigned cvt_pk_bf16(float lo, float hi) { unsigned r; asm volatile("v_cvt_pk_bf16_f32 %0, %1, %2" : "=v"(r) : "v"(lo), "v"(hi)); return r; }
; __device__ __forceinline__ float fsigmoid(float x) { return __builtin_amdgcn_rcpf(1.0f + __builtin_amdgcn_exp2f(-x * LOG2E)); }
; #define PG8_BAR __builtin_amdgcn_s_barrier()
;     __device__ __forceinline__ void operator()(const f32x4 (&acc)[2][2][4][2], const Unit& u, int wr, int wc, int fr, int fq) const {
;     ...
; #pragma unroll
;         for (int ai = 0; ai < 2; ++ai)
; #pragma unroll
;             for (int m = 0; m < 4; ++m) { const size_t row = (size_t)(row0 + ai * HALF + m * 16); const float rs = rsv[ai][m]; float r[8];
; #pragma unroll
;                 for (int n = 0; n < 2; ++n) { const f32x4 g = acc[ai][0][m][n] * rs, up = acc[ai][1][m][n] * rs;
; #pragma unroll
;                     for (int e = 0; e < 4; ++e) r[4 * n + e] = g[e] * fsigmoid(g[e]) * up[e]; }
;                 u32x4 w; w.x = cvt_pk_bf16(r[0], r[1]); w.y = cvt_pk_bf16(r[2], r[3]); w.z = cvt_pk_bf16(r[4], r[5]); w.w = cvt_pk_bf16(r[6], r[7]);
;                 gst((u32x4*)(U + row * ldu + f0), w); }
; template <class Epi, bool ALIGN_EPI>
; __device__ __forceinline__ void gemm_phase(LAS unsigned char* lds, const Gemm g, const StaticOrder& S, const Epi& E) {
;     ...
;         if (!has_next) break;
; #pragma unroll
;         for (int a = 0; a < 2; ++a)
; #pragma unroll
;             for (int b = 0; b < 2; ++b)
; #pragma unroll
;                 for (int m = 0; m < 4; ++m)
; #pragma unroll
;                     for (int n = 0; n < 2; ++n) acc[a][b][m][n] = (f32x4){0.f, 0.f, 0.f, 0.f};
;         cur = nxt; cA = nA; cB = nB; ++ui;
;         if constexpr (ALIGN_EPI) { if (wr == 1) PG8_BAR; }
	s_nop 1
	v_mov_b32_e32 v34, v26
	v_mov_b32_e32 v35, v30
	v_pk_mul_f32 v[34:35], v[34:35], v[134:135] op_sel_hi:[1,0]
	v_mov_b32_e32 v30, v27
	v_mul_f32_e32 v26, 0xbfb8aa3b, v35
	v_exp_f32_e32 v26, v26
	s_nop 0
	v_add_f32_e32 v26, 1.0, v26
	v_rcp_f32_e32 v26, v26
	s_nop 0
	v_mul_f32_e32 v26, v35, v26
	v_mul_f32_e32 v34, v34, v26
	v_pk_mul_f32 v[26:27], v[30:31], v[134:135] op_sel_hi:[1,0]
	s_nop 0
	v_mul_f32_e32 v30, 0xbfb8aa3b, v27
	v_exp_f32_e32 v30, v30
	s_nop 0
	v_add_f32_e32 v30, 1.0, v30
	v_rcp_f32_e32 v30, v30
	s_nop 0
	v_mul_f32_e32 v27, v27, v30
	v_mul_f32_e32 v30, v26, v27
	v_mov_b32_e32 v26, v28
	v_mov_b32_e32 v27, v32
	v_pk_mul_f32 v[26:27], v[26:27], v[134:135] op_sel_hi:[1,0]
	v_mov_b32_e32 v32, v29
	v_mul_f32_e32 v28, 0xbfb8aa3b, v27
	v_exp_f32_e32 v28, v28
	s_nop 0
	v_add_f32_e32 v28, 1.0, v28
	v_rcp_f32_e32 v28, v28
	s_nop 0
	v_mul_f32_e32 v27, v27, v28
	v_mul_f32_e32 v28, v26, v27
	v_pk_mul_f32 v[26:27], v[32:33], v[134:135] op_sel_hi:[1,0]
	s_nop 0
	v_mul_f32_e32 v29, 0xbfb8aa3b, v27
	v_exp_f32_e32 v29, v29
	s_nop 0
	v_add_f32_e32 v29, 1.0, v29
	v_rcp_f32_e32 v29, v29
	s_nop 0
	v_mul_f32_e32 v27, v27, v29
	v_mul_f32_e32 v29, v26, v27
	v_mov_b32_e32 v26, v18
	v_mov_b32_e32 v27, v22
	v_pk_mul_f32 v[26:27], v[26:27], v[134:135] op_sel_hi:[1,0]
	v_mov_b32_e32 v22, v19
	v_mul_f32_e32 v18, 0xbfb8aa3b, v27
	v_exp_f32_e32 v18, v18
	s_nop 0
	v_add_f32_e32 v18, 1.0, v18
	v_rcp_f32_e32 v18, v18
	s_nop 0
	v_mul_f32_e32 v18, v27, v18
	v_mul_f32_e32 v26, v26, v18
	v_pk_mul_f32 v[18:19], v[22:23], v[134:135] op_sel_hi:[1,0]
	s_nop 0
	v_mul_f32_e32 v22, 0xbfb8aa3b, v19
	v_exp_f32_e32 v22, v22
	s_nop 0
	v_add_f32_e32 v22, 1.0, v22
	v_rcp_f32_e32 v22, v22
	s_nop 0
	v_mul_f32_e32 v19, v19, v22
	v_mul_f32_e32 v22, v18, v19
	v_mov_b32_e32 v18, v20
	v_mov_b32_e32 v19, v24
	v_pk_mul_f32 v[18:19], v[18:19], v[134:135] op_sel_hi:[1,0]
	v_mov_b32_e32 v24, v21
	v_mul_f32_e32 v20, 0xbfb8aa3b, v19
	v_exp_f32_e32 v20, v20
	s_nop 0
	v_add_f32_e32 v20, 1.0, v20
	v_rcp_f32_e32 v20, v20
	s_nop 0
	v_mul_f32_e32 v19, v19, v20
	v_mul_f32_e32 v23, v18, v19
	v_pk_mul_f32 v[18:19], v[24:25], v[134:135] op_sel_hi:[1,0]
	s_nop 0
	v_mul_f32_e32 v20, 0xbfb8aa3b, v19
	v_exp_f32_e32 v20, v20
	s_nop 0
	v_add_f32_e32 v20, 1.0, v20
	v_rcp_f32_e32 v20, v20
	s_nop 0
	v_mul_f32_e32 v19, v19, v20
	v_mul_f32_e32 v21, v18, v19
	v_cvt_pk_bf16_f32 v18, v34, v30
	v_cvt_pk_bf16_f32 v19, v28, v29
	v_cvt_pk_bf16_f32 v20, v26, v22
	v_cvt_pk_bf16_f32 v21, v23, v21
	v_mad_i64_i32 v[22:23], s[20:21], v156, s4, v[114:115]
	v_lshl_add_u64 v[22:23], v[22:23], 0, v[116:117]
	global_store_dwordx4 v[22:23], v[18:21], off
	s_nop 1
	v_mov_b32_e32 v18, v10
	v_mov_b32_e32 v19, v14
	v_pk_mul_f32 v[18:19], v[18:19], v[130:131] op_sel_hi:[1,0]
	v_mov_b32_e32 v14, v11
	v_mul_f32_e32 v10, 0xbfb8aa3b, v19
	v_exp_f32_e32 v10, v10
	s_nop 0
	v_add_f32_e32 v10, 1.0, v10
	v_rcp_f32_e32 v10, v10
	s_nop 0
	v_mul_f32_e32 v10, v19, v10
	v_mul_f32_e32 v18, v18, v10
	v_pk_mul_f32 v[10:11], v[14:15], v[130:131] op_sel_hi:[1,0]
	s_nop 0
	v_mul_f32_e32 v14, 0xbfb8aa3b, v11
	v_exp_f32_e32 v14, v14
	s_nop 0
	v_add_f32_e32 v14, 1.0, v14
	v_rcp_f32_e32 v14, v14
	s_nop 0
	v_mul_f32_e32 v11, v11, v14
	v_mul_f32_e32 v14, v10, v11
	v_mov_b32_e32 v10, v12
	v_mov_b32_e32 v11, v16
	v_pk_mul_f32 v[10:11], v[10:11], v[130:131] op_sel_hi:[1,0]
	v_mov_b32_e32 v16, v13
	v_mul_f32_e32 v12, 0xbfb8aa3b, v11
	v_exp_f32_e32 v12, v12
	s_nop 0
	v_add_f32_e32 v12, 1.0, v12
	v_rcp_f32_e32 v12, v12
	s_nop 0
	v_mul_f32_e32 v11, v11, v12
	v_mul_f32_e32 v12, v10, v11
	v_pk_mul_f32 v[10:11], v[16:17], v[130:131] op_sel_hi:[1,0]
	s_nop 0
	v_mul_f32_e32 v13, 0xbfb8aa3b, v11
	v_exp_f32_e32 v13, v13
	s_nop 0
	v_add_f32_e32 v13, 1.0, v13
	v_rcp_f32_e32 v13, v13
	s_nop 0
	v_mul_f32_e32 v11, v11, v13
	v_mul_f32_e32 v13, v10, v11
	v_mov_b32_e32 v10, v0
	v_mov_b32_e32 v11, v6
	v_pk_mul_f32 v[10:11], v[10:11], v[130:131] op_sel_hi:[1,0]
	v_mov_b32_e32 v6, v1
	v_mul_f32_e32 v0, 0xbfb8aa3b, v11
	v_exp_f32_e32 v0, v0
	s_nop 0
	v_add_f32_e32 v0, 1.0, v0
	v_rcp_f32_e32 v0, v0
	s_nop 0
	v_mul_f32_e32 v0, v11, v0
	v_mul_f32_e32 v10, v10, v0
	v_pk_mul_f32 v[0:1], v[6:7], v[130:131] op_sel_hi:[1,0]
	s_nop 0
	v_mul_f32_e32 v6, 0xbfb8aa3b, v1
	v_exp_f32_e32 v6, v6
	s_nop 0
	v_add_f32_e32 v6, 1.0, v6
	v_rcp_f32_e32 v6, v6
	s_nop 0
	v_mul_f32_e32 v1, v1, v6
	v_mul_f32_e32 v6, v0, v1
	v_mov_b32_e32 v0, v2
	v_mov_b32_e32 v1, v8
	v_pk_mul_f32 v[0:1], v[0:1], v[130:131] op_sel_hi:[1,0]
	v_mov_b32_e32 v8, v3
	v_mul_f32_e32 v2, 0xbfb8aa3b, v1
	v_exp_f32_e32 v2, v2
	s_nop 0
	v_add_f32_e32 v2, 1.0, v2
	v_rcp_f32_e32 v2, v2
	s_nop 0
	v_mul_f32_e32 v1, v1, v2
	v_mul_f32_e32 v7, v0, v1
	v_pk_mul_f32 v[0:1], v[8:9], v[130:131] op_sel_hi:[1,0]
	s_nop 0
	v_mul_f32_e32 v2, 0xbfb8aa3b, v1
	v_exp_f32_e32 v2, v2
	s_nop 0
	v_add_f32_e32 v2, 1.0, v2
	v_rcp_f32_e32 v2, v2
	s_nop 0
	v_mul_f32_e32 v1, v1, v2
	v_mul_f32_e32 v3, v0, v1
	v_cvt_pk_bf16_f32 v0, v18, v14
	v_cvt_pk_bf16_f32 v1, v12, v13
	v_cvt_pk_bf16_f32 v2, v10, v6
	v_cvt_pk_bf16_f32 v3, v7, v3
	v_mad_i64_i32 v[6:7], s[20:21], v154, s4, v[114:115]
	v_lshl_add_u64 v[6:7], v[6:7], 0, v[116:117]
	s_mov_b64 s[20:21], -1
	global_store_dwordx4 v[6:7], v[0:3], off
	s_cbranch_vccnz .LBB0_1254
	s_andn2_b64 vcc, exec, s[70:71]
	s_cbranch_vccnz .LBB0_1253
	s_barrier
	s_branch .LBB0_1253
